# full-128B-line LDS-DMA pieces (8 rows x 128B) + XOR-swizzled LDS image for the up-GEMM K-loop
# speedup vs baseline: 1.0057x; 1.0057x over previous
; #define PG8_STAGE(bufoff, gbase, voff) do { _Pragma("unroll") for (int _i = 0; _i < 2; ++_i) \
;         __builtin_amdgcn_global_load_lds((const unsigned*)((const char*)(gbase) + (voff)[_i]), (PG8_LAS unsigned*)(lds + (bufoff) + ldsw + _i * 8192), 16, 0, 0); } while (0)
; #define PG8_BAR __builtin_amdgcn_s_barrier()
; template <class Epi, class Sched, bool ALIGN_EPI = false, bool SP2 = false>
; __device__ __forceinline__ void gemm_phase(PG8_LAS unsigned char* lds, const int tid, const Gemm g, const Sched& S, const Epi& E) {
;     const int wid = __builtin_amdgcn_readfirstlane(tid >> 6), lane = tid & 63, wr = wid >> 2, wc = wid & 3, fr = lane & 15, fq = lane >> 4;
;     const int K = g.K, nt = K / BK;
;     unsigned voffA[2], voffB[2];
; #pragma unroll
;     for (int i = 0; i < 2; ++i) { int R, C; stage_rc(tid * 16 + i * 8192, R, C); const int Rb = Epi::PERM ? ((R & ~31) + perm32(R & 31)) : R;
;         voffA[i] = (unsigned)(R * K + C) * 2u; voffB[i] = (unsigned)(Rb * K + C) * 2u; }
;     const size_t kstep = (size_t)(BK * 2);
;     const size_t hstep = (size_t)HALF * K * 2;
;     const size_t tstep = 2 * hstep;
;     const unsigned ldsw = (unsigned)wid * 1024u;
;     const int aoff = lds_byte(wr * 64 + fr, fq * 8), boff = lds_byte(wc * 32 + fr, fq * 8);
;     ...
;     if constexpr (SP2) {
;         PG8_STAGE(PG8_SB(0, 0), cB, voffB); PG8_STAGE(PG8_SB(0, 1), cB + hstep, voffB); PG8_STAGE(PG8_SA(0, 0), cA, voffA); PG8_STAGE(PG8_SA(0, 1), cA + hstep, voffA);
;         if (wr == 1) PG8_BAR;
.LBB0_414:
	s_and_b64 vcc, exec, s[0:1]
	s_cbranch_vccz .LBB0_433
	v_readlane_b32 s0, v252, 24
	v_readlane_b32 s1, v252, 25
	s_andn2_b64 vcc, exec, s[0:1]
	v_readfirstlane_b32 s4, v184
	s_cbranch_vccnz .LBB0_433
	v_lshrrev_b32_e32 v236, 3, v182
	v_and_b32_e32 v237, 6, v236
	v_and_b32_e32 v238, 7, v182
	v_xor_b32_e32 v238, v238, v237
	v_lshlrev_b32_e32 v238, 4, v238
	s_lshr_b32 s90, s4, 6
	s_lshl_b32 s91, s90, 3
	v_add_u32_e32 v239, s91, v236
	v_lshl_add_u32 v244, v239, 11, v238
	v_add_u32_e32 v245, 0x20000, v244
	v_and_b32_e32 v240, 31, v239
	v_bfe_u32 v241, v240, 2, 2
	v_lshlrev_b32_e32 v241, 3, v241
	v_bfe_u32 v242, v240, 4, 1
	v_lshl_or_b32 v241, v242, 2, v241
	v_and_b32_e32 v242, 3, v240
	v_or_b32_e32 v241, v241, v242
	v_and_b32_e32 v242, 32, v239
	v_or_b32_e32 v241, v241, v242
	v_lshl_add_u32 v246, v241, 11, v238
	v_add_u32_e32 v247, 0x20000, v246
	v_and_b32_e32 v236, 15, v182
	v_lshrrev_b32_e32 v237, 4, v182
	v_and_b32_e32 v239, 6, v236
	v_xor_b32_e32 v237, v237, v239
	v_lshlrev_b32_e32 v237, 4, v237
	v_and_b32_e32 v239, 7, v236
	v_lshl_or_b32 v237, v239, 7, v237
	v_bfe_u32 v239, v236, 3, 1
	v_lshl_or_b32 v237, v239, 10, v237
	s_lshr_b32 s92, s4, 8
	s_lshl_b32 s92, s92, 13
	v_add_u32_e32 v248, s92, v237
	v_xor_b32_e32 v249, 64, v248
	s_bfe_u32 s93, s4, 0x20006
	s_lshl_b32 s93, s93, 12
	v_add_u32_e32 v254, s93, v237
	v_xor_b32_e32 v255, 64, v254
	v_lshlrev_b32_e32 v0, 4, v184
	s_waitcnt lgkmcnt(0)
	v_add_u32_e32 v1, 0x2000, v0
	v_ashrrev_i32_e32 v2, 31, v1
	v_lshrrev_b32_e32 v2, 22, v2
	v_add_u32_e32 v2, v1, v2
	v_ashrrev_i32_e32 v8, 10, v2
	v_mul_i32_i24_e32 v2, 0x400, v8
	v_sub_u32_e32 v1, v1, v2
	v_lshrrev_b32_e32 v2, 4, v1
	v_bitop3_b32 v1, v2, v1, 32 bitop3:0x6c
	s_cmp_eq_u32 s7, 6
	v_ashrrev_i32_e32 v2, 31, v1
	s_cselect_b64 s[0:1], -1, 0
	v_lshrrev_b32_e32 v2, 26, v2
	s_and_b64 s[2:3], s[0:1], exec
	v_add_u32_e32 v2, v1, v2
	v_lshlrev_b32_e32 v3, 3, v8
	s_cselect_b32 s2, 0x2c00000, 0
	v_readlane_b32 s3, v251, 50
	v_ashrrev_i32_e32 v9, 6, v2
	v_and_b32_e32 v3, -16, v3
	s_add_u32 s10, s3, s2
	v_readlane_b32 s2, v251, 51
	v_add_u32_e32 v3, v9, v3
	s_addc_u32 s11, s2, 0
	v_and_b32_e32 v4, 3, v9
	s_mov_b32 s2, 0x1fffe0
	v_lshrrev_b32_e32 v5, 2, v3
	v_lshlrev_b32_e32 v6, 1, v3
	v_and_b32_e32 v2, 0xc0, v2
	v_and_or_b32 v4, v3, s2, v4
	v_and_b32_e32 v5, 4, v5
	v_and_b32_e32 v6, 24, v6
	v_sub_u32_e32 v1, v1, v2
	v_or3_b32 v4, v4, v5, v6
	v_lshlrev_b32_e32 v5, 5, v8
	v_ashrrev_i16_sdwa v1, v223, sext(v1) dst_sel:DWORD dst_unused:UNUSED_PAD src0_sel:DWORD src1_sel:BYTE_0
	v_and_b32_e32 v5, 32, v5
	v_bfe_i32 v10, v1, 0, 16
	v_add_lshl_u32 v1, v5, v10, 1
	v_mov_b32_e32 v144, v247
	v_mov_b32_e32 v146, v245
	v_bfe_i32 v1, v184, 27, 1
	v_lshrrev_b32_e32 v1, 22, v1
	v_add_u32_e32 v1, v0, v1
	v_and_b32_e32 v1, 0xfffffc00, v1
	v_sub_u32_e32 v0, v0, v1
	v_lshrrev_b32_e32 v1, 4, v0
	v_ashrrev_i32_e32 v2, 31, v184
	v_bitop3_b32 v0, v1, v0, 32 bitop3:0x6c
	v_lshrrev_b32_e32 v2, 26, v2
	v_ashrrev_i32_e32 v1, 31, v0
	v_add_u32_e32 v2, v184, v2
	v_lshrrev_b32_e32 v1, 26, v1
	v_ashrrev_i32_e32 v12, 6, v2
	v_add_u32_e32 v1, v0, v1
	v_lshlrev_b32_e32 v2, 3, v12
	v_ashrrev_i32_e32 v11, 6, v1
	v_and_b32_e32 v2, -16, v2
	s_ashr_i32 s18, s4, 6
	v_add_u32_e32 v2, v11, v2
	v_and_b32_e32 v3, 3, v11
	s_ashr_i32 s5, s4, 8
	s_lshl_b32 s12, s18, 10
	v_and_or_b32 v3, v2, s2, v3
	v_lshrrev_b32_e32 v4, 2, v2
	v_lshlrev_b32_e32 v5, 1, v2
	v_and_b32_e32 v1, 0xc0, v1
	v_readlane_b32 s2, v253, 53
	v_and_b32_e32 v4, 4, v4
	v_and_b32_e32 v5, 24, v5
	v_sub_u32_e32 v0, v0, v1
	v_readlane_b32 s3, v253, 54
	s_add_u32 s2, s10, s2
	v_or3_b32 v3, v3, v4, v5
	v_lshlrev_b32_e32 v4, 5, v12
	v_ashrrev_i16_sdwa v0, v223, sext(v0) dst_sel:DWORD dst_unused:UNUSED_PAD src0_sel:DWORD src1_sel:BYTE_0
	s_addc_u32 s3, s11, s3
	v_readlane_b32 s6, v251, 21
	v_and_b32_e32 v4, 32, v4
	v_bfe_i32 v13, v0, 0, 16
	s_add_u32 s24, s2, s6
	v_readlane_b32 s2, v251, 20
	v_add_lshl_u32 v0, v4, v13, 1
	s_addc_u32 s25, s3, s2
	s_add_i32 s14, s12, 0
	v_mov_b32_e32 v168, v246
	s_add_i32 m0, s14, 0x10000
	v_readlane_b32 s20, v251, 16
	global_load_lds_dwordx4 v168, s[24:25]
	s_add_i32 m0, s14, 0x12000
	s_add_u32 s2, s24, 0x40000
	global_load_lds_dwordx4 v144, s[24:25]
	s_addc_u32 s3, s25, 0
	s_add_i32 m0, s14, 0x14000
	v_readlane_b32 s21, v251, 17
	global_load_lds_dwordx4 v168, s[2:3]
	s_add_i32 m0, s14, 0x16000
	v_mov_b32_e32 v148, v244
	global_load_lds_dwordx4 v144, s[2:3]
	v_readlane_b32 s2, v253, 63
	v_readlane_b32 s3, v251, 0
	s_add_u32 s26, s20, s2
	s_addc_u32 s27, s21, s3
	s_add_i32 s15, s14, 0x2000
	s_mov_b32 m0, s14
	s_add_u32 s2, s26, 0x40000
	global_load_lds_dwordx4 v148, s[26:27]
	s_mov_b32 m0, s15
	s_addc_u32 s3, s27, 0
	s_add_i32 s16, s14, 0x4000
	global_load_lds_dwordx4 v146, s[26:27]
	s_mov_b32 m0, s16
	s_add_i32 s17, s14, 0x6000
	global_load_lds_dwordx4 v148, s[2:3]
	s_mov_b32 m0, s17
	v_mov_b32_e32 v145, v169
	global_load_lds_dwordx4 v146, s[2:3]
	v_mov_b32_e32 v149, v169
	v_mov_b32_e32 v147, v169
	s_cmp_eq_u32 s5, 1
	s_mov_b64 s[54:55], s[28:29]
	v_lshl_add_u64 v[6:7], s[24:25], 0, v[168:169]
	v_lshl_add_u64 v[4:5], s[24:25], 0, v[144:145]
	v_lshl_add_u64 v[0:1], s[26:27], 0, v[148:149]
	s_cselect_b64 s[2:3], -1, 0
	s_cmp_lg_u32 s5, 1
	v_lshl_add_u64 v[2:3], s[26:27], 0, v[146:147]
	v_readlane_b32 s22, v251, 18
	v_readlane_b32 s23, v251, 19
	s_cbranch_scc1 .LBB0_418
	s_barrier
; #define PG8_STAGE(bufoff, gbase, voff) do { _Pragma("unroll") for (int _i = 0; _i < 2; ++_i) \
;         __builtin_amdgcn_global_load_lds((const unsigned*)((const char*)(gbase) + (voff)[_i]), (PG8_LAS unsigned*)(lds + (bufoff) + ldsw + _i * 8192), 16, 0, 0); } while (0)
; #define PG8_WAIT_V(n) asm volatile("s_waitcnt vmcnt(" #n ")" ::: "memory")
; #define PG8_BAR __builtin_amdgcn_s_barrier()
; template <class Epi, class Sched, bool ALIGN_EPI = false, bool SP2 = false>
; __device__ __forceinline__ void gemm_phase(PG8_LAS unsigned char* lds, const int tid, const Gemm g, const Sched& S, const Epi& E) {
;     ...
;     if constexpr (SP2) {
;         PG8_STAGE(PG8_SB(0, 0), cB, voffB); PG8_STAGE(PG8_SB(0, 1), cB + hstep, voffB); PG8_STAGE(PG8_SA(0, 0), cA, voffA); PG8_STAGE(PG8_SA(0, 1), cA + hstep, voffA);
;         if (wr == 1) PG8_BAR;
;         PG8_WAIT_V(2); PG8_BAR;
;         PG8_STAGE(PG8_SB(1, 0), cB + kstep, voffB); PG8_STAGE(PG8_SA(1, 0), cA + kstep, voffA); PG8_STAGE(PG8_SB(1, 1), cB + hstep + kstep, voffB);
;         PG8_WAIT_V(6); PG8_BAR;
.LBB0_418:
	s_and_b64 s[0:1], s[0:1], exec
	v_readlane_b32 s6, v251, 52
	s_cselect_b32 s0, 2, 0
	s_mul_i32 s1, s6, 3
	s_add_i32 s0, s0, s1
	v_readlane_b32 s7, v251, 53
	s_ashr_i32 s1, s0, 31
	s_lshl_b64 s[6:7], s[0:1], 17
	s_add_u32 s6, s8, s6
	s_addc_u32 s7, s9, s7
	s_mul_hi_i32 s1, s0, 0x16000
	s_mul_i32 s0, s0, 0x16000
	v_readlane_b32 s8, v251, 46
	s_add_u32 s8, s8, s0
	v_readlane_b32 s0, v251, 47
	s_addc_u32 s9, s0, s1
	s_lshl_b32 s0, s18, 5
	s_and_b32 s22, s0, 0x60
	s_add_i32 m0, s14, 0x18000
	v_lshl_add_u64 v[6:7], v[6:7], 0, s[36:37]
	s_lshl_b32 s21, s5, 13
	s_lshl_b32 s23, s22, 7
	s_waitcnt vmcnt(2)
	s_barrier
	global_load_lds_dwordx4 v[6:7], off
	v_lshl_add_u64 v[4:5], v[4:5], 0, s[36:37]
	s_add_i32 m0, s14, 0x1a000
	s_add_i32 s18, s14, 0x8000
	s_add_i32 s19, s14, 0xa000
	global_load_lds_dwordx4 v[4:5], off
	v_lshl_add_u64 v[0:1], v[0:1], 0, s[36:37]
	s_mov_b32 m0, s18
	s_add_u32 s0, s24, 0x40080
	global_load_lds_dwordx4 v[0:1], off
	v_lshl_add_u64 v[0:1], v[2:3], 0, s[36:37]
	s_mov_b32 m0, s19
	s_addc_u32 s1, s25, 0
	global_load_lds_dwordx4 v[0:1], off
	s_add_i32 m0, s14, 0x1c000
	v_lshl_add_u64 v[0:1], s[0:1], 0, v[168:169]
	global_load_lds_dwordx4 v[0:1], off
	v_lshl_add_u64 v[0:1], s[0:1], 0, v[144:145]
	s_add_i32 m0, s14, 0x1e000
	s_cmpk_lt_u32 s4, 0x100
	global_load_lds_dwordx4 v[0:1], off
	v_lshrrev_b32_e32 v0, 1, v182
	v_and_b32_e32 v0, 24, v0
	v_and_b32_e32 v1, 15, v182
	v_lshlrev_b32_e32 v2, 1, v0
	v_lshl_or_b32 v158, s5, 6, v1
	v_lshl_or_b32 v1, v1, 6, v2
	v_lshlrev_b32_e32 v2, 2, v182
	v_and_b32_e32 v2, 32, v2
	v_bitop3_b32 v3, v1, s21, v2 bitop3:0xde
	v_mov_b32_e32 v159, v254
	v_lshlrev_b32_e32 v1, 14, v12
	v_and_b32_e32 v1, 0xffff8000, v1
	v_lshl_add_u32 v1, v11, 11, v1
	v_and_b32_e32 v2, 1, v12
	v_lshl_or_b32 v1, v2, 6, v1
	v_mov_b32_e32 v150, v244
	v_lshlrev_b32_e32 v1, 14, v8
	v_and_b32_e32 v1, 0xffff8000, v1
	s_waitcnt vmcnt(6)
	v_lshl_add_u32 v1, v9, 11, v1
	v_and_b32_e32 v2, 1, v8
	v_lshl_or_b32 v1, v2, 6, v1
	v_readlane_b32 s0, v253, 61
	s_mov_b32 s20, 0
	s_cselect_b64 s[28:29], -1, 0
	v_or_b32_e32 v160, s22, v0
	v_mov_b32_e32 v151, v169
	v_mov_b32_e32 v152, v245
	v_mov_b32_e32 v153, v169
	v_mov_b32_e32 v161, v248
	s_lshl_b32 s21, s22, 2
	v_lshlrev_b32_e32 v162, 2, v0
	v_readlane_b32 s22, v253, 52
	s_mov_b32 s23, s0
	s_barrier
	v_readlane_b32 s1, v253, 62
	s_branch .LBB0_421

; #define PG8_STAGE(bufoff, gbase, voff) do { _Pragma("unroll") for (int _i = 0; _i < 2; ++_i) \
;         __builtin_amdgcn_global_load_lds((const unsigned*)((const char*)(gbase) + (voff)[_i]), (PG8_LAS unsigned*)(lds + (bufoff) + ldsw + _i * 8192), 16, 0, 0); } while (0)
; #define PG8_LDA(dst, b, h) do { _Pragma("unroll") for (int m = 0; m < 4; ++m) _Pragma("unroll") for (int k = 0; k < 2; ++k) dst[m][k] = *(const PG8_LAS bf16x8*)(lds + PG8_SA(b, h) + aoff + m * 2048 + k * 1024); } while (0)
; #define PG8_LDB(dst, b, h) do { _Pragma("unroll") for (int n = 0; n < 2; ++n) _Pragma("unroll") for (int k = 0; k < 2; ++k) dst[n][k] = *(const PG8_LAS bf16x8*)(lds + PG8_SB(b, h) + boff + n * 2048 + k * 1024); } while (0)
; #define PG8_MMA(ai, bj, At, Bt) do { __builtin_amdgcn_s_setprio(1); _Pragma("unroll") for (int m = 0; m < 4; ++m) _Pragma("unroll") for (int n = 0; n < 2; ++n) _Pragma("unroll") for (int k = 0; k < 2; ++k) \
;         acc[ai][bj][m][n] = __builtin_amdgcn_mfma_f32_16x16x32_bf16(Bt[n][k], At[m][k], acc[ai][bj][m][n], 0, 0, 0); __builtin_amdgcn_s_setprio(0); } while (0)
; #define PG8_WAIT_V(n) asm volatile("s_waitcnt vmcnt(" #n ")" ::: "memory")
; #define PG8_WAIT_L(n) asm volatile("s_waitcnt lgkmcnt(" #n ")" ::: "memory")
; #define PG8_BAR __builtin_amdgcn_s_barrier()
; #define PG8_SCHED __builtin_amdgcn_sched_barrier(0)
; template <class Epi, class Sched, bool ALIGN_EPI = false, bool SP2 = false>
; __device__ __forceinline__ void gemm_phase(PG8_LAS unsigned char* lds, const int tid, const Gemm g, const Sched& S, const Epi& E) {
;     ...
;             PG8_LDB(B0, 0, 0); PG8_LDB(B1, 0, 1); PG8_SCHED; PG8_LDA(At, 0, 0); PG8_STAGE(PG8_SA(1, 1), a1 + hstep, voffA);
;             PG8_WAIT_V(8); PG8_WAIT_L(0); PG8_BAR; PG8_MMA(0, 0, At, B0); PG8_MMA(0, 1, At, B1); PG8_BAR; PG8_SCHED;
;             PG8_LDA(At, 0, 1); PG8_STAGE(PG8_SB(0, 0), b2, voffB); PG8_STAGE(PG8_SB(0, 1), b2 + hstep, voffB); PG8_STAGE(PG8_SA(0, 0), a2, voffA);
;             PG8_WAIT_V(8); PG8_WAIT_L(0); PG8_BAR; PG8_MMA(1, 0, At, B0); PG8_MMA(1, 1, At, B1); PG8_BAR; PG8_SCHED;
.LBB0_426:
	s_add_u32 s24, s4, 0xfffc0080
	s_addc_u32 s25, s5, -1
	s_add_i32 s49, 0, 0x10000
	s_cmp_eq_u32 s48, 12
	s_cselect_b32 s27, s39, s25
	s_cselect_b32 s26, s41, s24
	s_cselect_b32 s25, s43, s47
	s_cselect_b32 s24, s42, s46
	s_add_i32 s52, 0, 0x14000
	v_add_u32_e32 v76, s49, v159
	v_add_u32_e32 v244, s49, v255
	v_add_u32_e32 v163, s52, v159
	v_add_u32_e32 v245, s52, v255
	ds_read_b128 v[64:67], v76
	ds_read_b128 v[68:71], v244
	ds_read_b128 v[72:75], v76 offset:2048
	ds_read_b128 v[76:79], v244 offset:2048
	ds_read_b128 v[154:157], v163
	ds_read_b128 v[164:167], v245
	ds_read_b128 v[186:189], v163 offset:2048
	ds_read_b128 v[190:193], v245 offset:2048
	v_lshl_add_u64 v[234:235], s[4:5], 0, v[150:151]
	s_add_i32 m0, s14, 0xc000
	ds_read_b128 v[194:197], v161
	ds_read_b128 v[198:201], v249
	ds_read_b128 v[202:205], v161 offset:2048
	ds_read_b128 v[206:209], v249 offset:2048
	ds_read_b128 v[210:213], v161 offset:4096
	ds_read_b128 v[214:217], v249 offset:4096
	ds_read_b128 v[218:221], v161 offset:6144
	ds_read_b128 v[230:233], v249 offset:6144
	global_load_lds_dwordx4 v[234:235], off
	v_lshl_add_u64 v[234:235], s[4:5], 0, v[152:153]
	s_add_i32 m0, s14, 0xe000
	s_nop 0
	global_load_lds_dwordx4 v[234:235], off
	s_waitcnt vmcnt(8)
	s_waitcnt lgkmcnt(0)
	s_barrier
	s_setprio 1
	s_waitcnt lgkmcnt(0)
	v_mfma_f32_16x16x32_bf16 v[140:143], v[64:67], v[194:197], v[140:143]
	v_mfma_f32_16x16x32_bf16 v[136:139], v[72:75], v[194:197], v[136:139]
	v_mfma_f32_16x16x32_bf16 v[124:127], v[64:67], v[202:205], v[124:127]
	v_mfma_f32_16x16x32_bf16 v[120:123], v[72:75], v[202:205], v[120:123]
	v_mfma_f32_16x16x32_bf16 v[108:111], v[64:67], v[210:213], v[108:111]
	v_mfma_f32_16x16x32_bf16 v[104:107], v[72:75], v[210:213], v[104:107]
	v_mfma_f32_16x16x32_bf16 v[92:95], v[64:67], v[218:221], v[92:95]
	v_mfma_f32_16x16x32_bf16 v[88:91], v[72:75], v[218:221], v[88:91]
	v_mfma_f32_16x16x32_bf16 v[140:143], v[68:71], v[198:201], v[140:143]
	v_mfma_f32_16x16x32_bf16 v[136:139], v[76:79], v[198:201], v[136:139]
	v_mfma_f32_16x16x32_bf16 v[124:127], v[68:71], v[206:209], v[124:127]
	v_mfma_f32_16x16x32_bf16 v[120:123], v[76:79], v[206:209], v[120:123]
	v_mfma_f32_16x16x32_bf16 v[108:111], v[68:71], v[214:217], v[108:111]
	v_mfma_f32_16x16x32_bf16 v[104:107], v[76:79], v[214:217], v[104:107]
	v_mfma_f32_16x16x32_bf16 v[92:95], v[68:71], v[230:233], v[92:95]
	v_mfma_f32_16x16x32_bf16 v[88:91], v[76:79], v[230:233], v[88:91]
	s_setprio 0
	s_setprio 1
	v_mfma_f32_16x16x32_bf16 v[132:135], v[154:157], v[194:197], v[132:135]
	v_mfma_f32_16x16x32_bf16 v[128:131], v[186:189], v[194:197], v[128:131]
	v_mfma_f32_16x16x32_bf16 v[116:119], v[154:157], v[202:205], v[116:119]
	v_mfma_f32_16x16x32_bf16 v[112:115], v[186:189], v[202:205], v[112:115]
	v_mfma_f32_16x16x32_bf16 v[100:103], v[154:157], v[210:213], v[100:103]
	v_mfma_f32_16x16x32_bf16 v[96:99], v[186:189], v[210:213], v[96:99]
	v_mfma_f32_16x16x32_bf16 v[84:87], v[154:157], v[218:221], v[84:87]
	v_mfma_f32_16x16x32_bf16 v[80:83], v[186:189], v[218:221], v[80:83]
	v_mfma_f32_16x16x32_bf16 v[132:135], v[164:167], v[198:201], v[132:135]
	v_mfma_f32_16x16x32_bf16 v[128:131], v[190:193], v[198:201], v[128:131]
	v_mfma_f32_16x16x32_bf16 v[116:119], v[164:167], v[206:209], v[116:119]
	v_mfma_f32_16x16x32_bf16 v[112:115], v[190:193], v[206:209], v[112:115]
	v_mfma_f32_16x16x32_bf16 v[100:103], v[164:167], v[214:217], v[100:103]
	v_mfma_f32_16x16x32_bf16 v[96:99], v[190:193], v[214:217], v[96:99]
	v_mfma_f32_16x16x32_bf16 v[84:87], v[164:167], v[230:233], v[84:87]
	v_mfma_f32_16x16x32_bf16 v[80:83], v[190:193], v[230:233], v[80:83]
	s_setprio 0
	s_barrier
	s_add_i32 s49, s49, s12
	v_lshl_add_u64 v[234:235], s[24:25], 0, v[168:169]
	s_mov_b32 m0, s49
	ds_read_b128 v[194:197], v161 offset:16384
	ds_read_b128 v[198:201], v249 offset:16384
	ds_read_b128 v[202:205], v161 offset:18432
	ds_read_b128 v[206:209], v249 offset:18432
	ds_read_b128 v[210:213], v161 offset:20480
	ds_read_b128 v[214:217], v249 offset:20480
	ds_read_b128 v[218:221], v161 offset:22528
	ds_read_b128 v[230:233], v249 offset:22528
	global_load_lds_dwordx4 v[234:235], off
	s_add_i32 m0, s49, 0x2000
	s_add_u32 s50, s24, 0x40000
	v_lshl_add_u64 v[236:237], s[24:25], 0, v[144:145]
	s_addc_u32 s51, s25, 0
	s_add_i32 s49, s52, s12
	global_load_lds_dwordx4 v[236:237], off
	v_lshl_add_u64 v[238:239], s[50:51], 0, v[168:169]
	s_mov_b32 m0, s49
	v_lshl_add_u64 v[240:241], s[26:27], 0, v[146:147]
	global_load_lds_dwordx4 v[238:239], off
	v_lshl_add_u64 v[238:239], s[50:51], 0, v[144:145]
	s_add_i32 m0, s49, 0x2000
	s_nop 0
	global_load_lds_dwordx4 v[238:239], off
	v_lshl_add_u64 v[238:239], s[26:27], 0, v[148:149]
	s_mov_b32 m0, s14
	s_nop 0
	global_load_lds_dwordx4 v[238:239], off
	s_mov_b32 m0, s15
	s_nop 0
	global_load_lds_dwordx4 v[240:241], off
	s_waitcnt vmcnt(8)
	s_waitcnt lgkmcnt(0)
	s_barrier
; #define PG8_STAGE(bufoff, gbase, voff) do { _Pragma("unroll") for (int _i = 0; _i < 2; ++_i) \
;         __builtin_amdgcn_global_load_lds((const unsigned*)((const char*)(gbase) + (voff)[_i]), (PG8_LAS unsigned*)(lds + (bufoff) + ldsw + _i * 8192), 16, 0, 0); } while (0)
; #define PG8_LDA(dst, b, h) do { _Pragma("unroll") for (int m = 0; m < 4; ++m) _Pragma("unroll") for (int k = 0; k < 2; ++k) dst[m][k] = *(const PG8_LAS bf16x8*)(lds + PG8_SA(b, h) + aoff + m * 2048 + k * 1024); } while (0)
; #define PG8_LDB(dst, b, h) do { _Pragma("unroll") for (int n = 0; n < 2; ++n) _Pragma("unroll") for (int k = 0; k < 2; ++k) dst[n][k] = *(const PG8_LAS bf16x8*)(lds + PG8_SB(b, h) + boff + n * 2048 + k * 1024); } while (0)
; #define PG8_MMA(ai, bj, At, Bt) do { __builtin_amdgcn_s_setprio(1); _Pragma("unroll") for (int m = 0; m < 4; ++m) _Pragma("unroll") for (int n = 0; n < 2; ++n) _Pragma("unroll") for (int k = 0; k < 2; ++k) \
;         acc[ai][bj][m][n] = __builtin_amdgcn_mfma_f32_16x16x32_bf16(Bt[n][k], At[m][k], acc[ai][bj][m][n], 0, 0, 0); __builtin_amdgcn_s_setprio(0); } while (0)
; #define PG8_WAIT_V(n) asm volatile("s_waitcnt vmcnt(" #n ")" ::: "memory")
; #define PG8_WAIT_L(n) asm volatile("s_waitcnt lgkmcnt(" #n ")" ::: "memory")
; #define PG8_BAR __builtin_amdgcn_s_barrier()
; #define PG8_SCHED __builtin_amdgcn_sched_barrier(0)
; template <class Epi, class Sched, bool ALIGN_EPI = false, bool SP2 = false>
; __device__ __forceinline__ void gemm_phase(PG8_LAS unsigned char* lds, const int tid, const Gemm g, const Sched& S, const Epi& E) {
;     ...
;             PG8_WAIT_V(8); PG8_WAIT_L(0); PG8_BAR; PG8_MMA(1, 0, At, B0); PG8_MMA(1, 1, At, B1); PG8_BAR; PG8_SCHED;
;             PG8_LDB(B0, 1, 0); PG8_LDB(B1, 1, 1); PG8_SCHED; PG8_LDA(At, 1, 0); PG8_STAGE(PG8_SA(0, 1), a2 + hstep, voffA);
;             PG8_WAIT_V(8); PG8_WAIT_L(0); PG8_BAR; PG8_MMA(0, 0, At, B0); PG8_MMA(0, 1, At, B1); PG8_BAR; PG8_SCHED;
	s_setprio 1
	s_waitcnt lgkmcnt(0)
	v_mfma_f32_16x16x32_bf16 v[60:63], v[64:67], v[194:197], v[60:63]
	v_mfma_f32_16x16x32_bf16 v[56:59], v[72:75], v[194:197], v[56:59]
	v_mfma_f32_16x16x32_bf16 v[44:47], v[64:67], v[202:205], v[44:47]
	v_mfma_f32_16x16x32_bf16 v[40:43], v[72:75], v[202:205], v[40:43]
	v_mfma_f32_16x16x32_bf16 v[28:31], v[64:67], v[210:213], v[28:31]
	v_mfma_f32_16x16x32_bf16 v[24:27], v[72:75], v[210:213], v[24:27]
	v_mfma_f32_16x16x32_bf16 v[12:15], v[64:67], v[218:221], v[12:15]
	v_mfma_f32_16x16x32_bf16 v[8:11], v[72:75], v[218:221], v[8:11]
	v_mfma_f32_16x16x32_bf16 v[60:63], v[68:71], v[198:201], v[60:63]
	v_mfma_f32_16x16x32_bf16 v[56:59], v[76:79], v[198:201], v[56:59]
	v_mfma_f32_16x16x32_bf16 v[44:47], v[68:71], v[206:209], v[44:47]
	v_mfma_f32_16x16x32_bf16 v[40:43], v[76:79], v[206:209], v[40:43]
	v_mfma_f32_16x16x32_bf16 v[28:31], v[68:71], v[214:217], v[28:31]
	v_mfma_f32_16x16x32_bf16 v[24:27], v[76:79], v[214:217], v[24:27]
	v_mfma_f32_16x16x32_bf16 v[12:15], v[68:71], v[230:233], v[12:15]
	v_mfma_f32_16x16x32_bf16 v[8:11], v[76:79], v[230:233], v[8:11]
	s_setprio 0
	s_setprio 1
	v_mfma_f32_16x16x32_bf16 v[52:55], v[154:157], v[194:197], v[52:55]
	v_mfma_f32_16x16x32_bf16 v[48:51], v[186:189], v[194:197], v[48:51]
	v_mfma_f32_16x16x32_bf16 v[36:39], v[154:157], v[202:205], v[36:39]
	v_mfma_f32_16x16x32_bf16 v[32:35], v[186:189], v[202:205], v[32:35]
	v_mfma_f32_16x16x32_bf16 v[20:23], v[154:157], v[210:213], v[20:23]
	v_mfma_f32_16x16x32_bf16 v[16:19], v[186:189], v[210:213], v[16:19]
	v_mfma_f32_16x16x32_bf16 v[4:7], v[154:157], v[218:221], v[4:7]
	v_mfma_f32_16x16x32_bf16 v[0:3], v[186:189], v[218:221], v[0:3]
	v_mfma_f32_16x16x32_bf16 v[52:55], v[164:167], v[198:201], v[52:55]
	v_mfma_f32_16x16x32_bf16 v[48:51], v[190:193], v[198:201], v[48:51]
	v_mfma_f32_16x16x32_bf16 v[36:39], v[164:167], v[206:209], v[36:39]
	v_mfma_f32_16x16x32_bf16 v[32:35], v[190:193], v[206:209], v[32:35]
	v_mfma_f32_16x16x32_bf16 v[20:23], v[164:167], v[214:217], v[20:23]
	v_mfma_f32_16x16x32_bf16 v[16:19], v[190:193], v[214:217], v[16:19]
	v_mfma_f32_16x16x32_bf16 v[4:7], v[164:167], v[230:233], v[4:7]
	v_mfma_f32_16x16x32_bf16 v[0:3], v[190:193], v[230:233], v[0:3]
	s_setprio 0
	s_barrier
	s_add_i32 s49, 0, 0x18000
	s_add_i32 s50, 0, 0x1c000
	v_add_u32_e32 v76, s49, v159
	v_add_u32_e32 v244, s49, v255
	v_add_u32_e32 v163, s50, v159
	v_add_u32_e32 v245, s50, v255
	ds_read_b128 v[64:67], v76
	ds_read_b128 v[68:71], v244
	ds_read_b128 v[72:75], v76 offset:2048
	ds_read_b128 v[76:79], v244 offset:2048
	ds_read_b128 v[154:157], v163
	ds_read_b128 v[164:167], v245
	ds_read_b128 v[186:189], v163 offset:2048
	ds_read_b128 v[190:193], v245 offset:2048
	s_add_u32 s26, s26, 0x40000
	s_addc_u32 s27, s27, 0
	s_mov_b32 m0, s16
	v_lshl_add_u64 v[242:243], s[26:27], 0, v[148:149]
	ds_read_b128 v[194:197], v161 offset:32768
	ds_read_b128 v[198:201], v249 offset:32768
	ds_read_b128 v[202:205], v161 offset:34816
	ds_read_b128 v[206:209], v249 offset:34816
	ds_read_b128 v[210:213], v161 offset:36864
	ds_read_b128 v[214:217], v249 offset:36864
	ds_read_b128 v[218:221], v161 offset:38912
	ds_read_b128 v[230:233], v249 offset:38912
	global_load_lds_dwordx4 v[242:243], off
	v_lshl_add_u64 v[242:243], s[26:27], 0, v[146:147]
	s_mov_b32 m0, s17
	s_nop 0
	global_load_lds_dwordx4 v[242:243], off
	s_waitcnt vmcnt(8)
	s_waitcnt lgkmcnt(0)
	s_barrier
	s_setprio 1
	s_waitcnt lgkmcnt(0)
	v_mfma_f32_16x16x32_bf16 v[140:143], v[64:67], v[194:197], v[140:143]
	v_mfma_f32_16x16x32_bf16 v[136:139], v[72:75], v[194:197], v[136:139]
	v_mfma_f32_16x16x32_bf16 v[124:127], v[64:67], v[202:205], v[124:127]
	v_mfma_f32_16x16x32_bf16 v[120:123], v[72:75], v[202:205], v[120:123]
	v_mfma_f32_16x16x32_bf16 v[108:111], v[64:67], v[210:213], v[108:111]
	v_mfma_f32_16x16x32_bf16 v[104:107], v[72:75], v[210:213], v[104:107]
	v_mfma_f32_16x16x32_bf16 v[92:95], v[64:67], v[218:221], v[92:95]
	v_mfma_f32_16x16x32_bf16 v[88:91], v[72:75], v[218:221], v[88:91]
	v_mfma_f32_16x16x32_bf16 v[140:143], v[68:71], v[198:201], v[140:143]
	v_mfma_f32_16x16x32_bf16 v[136:139], v[76:79], v[198:201], v[136:139]
	v_mfma_f32_16x16x32_bf16 v[124:127], v[68:71], v[206:209], v[124:127]
	v_mfma_f32_16x16x32_bf16 v[120:123], v[76:79], v[206:209], v[120:123]
	v_mfma_f32_16x16x32_bf16 v[108:111], v[68:71], v[214:217], v[108:111]
	v_mfma_f32_16x16x32_bf16 v[104:107], v[76:79], v[214:217], v[104:107]
	v_mfma_f32_16x16x32_bf16 v[92:95], v[68:71], v[230:233], v[92:95]
	v_mfma_f32_16x16x32_bf16 v[88:91], v[76:79], v[230:233], v[88:91]
	s_setprio 0
	s_setprio 1
	v_mfma_f32_16x16x32_bf16 v[132:135], v[154:157], v[194:197], v[132:135]
	v_mfma_f32_16x16x32_bf16 v[128:131], v[186:189], v[194:197], v[128:131]
	v_mfma_f32_16x16x32_bf16 v[116:119], v[154:157], v[202:205], v[116:119]
	v_mfma_f32_16x16x32_bf16 v[112:115], v[186:189], v[202:205], v[112:115]
	v_mfma_f32_16x16x32_bf16 v[100:103], v[154:157], v[210:213], v[100:103]
	v_mfma_f32_16x16x32_bf16 v[96:99], v[186:189], v[210:213], v[96:99]
	v_mfma_f32_16x16x32_bf16 v[84:87], v[154:157], v[218:221], v[84:87]
	v_mfma_f32_16x16x32_bf16 v[80:83], v[186:189], v[218:221], v[80:83]
	v_mfma_f32_16x16x32_bf16 v[132:135], v[164:167], v[198:201], v[132:135]
	v_mfma_f32_16x16x32_bf16 v[128:131], v[190:193], v[198:201], v[128:131]
	v_mfma_f32_16x16x32_bf16 v[116:119], v[164:167], v[206:209], v[116:119]
	v_mfma_f32_16x16x32_bf16 v[112:115], v[190:193], v[206:209], v[112:115]
	v_mfma_f32_16x16x32_bf16 v[100:103], v[164:167], v[214:217], v[100:103]
	v_mfma_f32_16x16x32_bf16 v[96:99], v[190:193], v[214:217], v[96:99]
	v_mfma_f32_16x16x32_bf16 v[84:87], v[164:167], v[230:233], v[84:87]
	v_mfma_f32_16x16x32_bf16 v[80:83], v[190:193], v[230:233], v[80:83]
	s_setprio 0
	s_barrier
; #define PG8_STAGE(bufoff, gbase, voff) do { _Pragma("unroll") for (int _i = 0; _i < 2; ++_i) \
;         __builtin_amdgcn_global_load_lds((const unsigned*)((const char*)(gbase) + (voff)[_i]), (PG8_LAS unsigned*)(lds + (bufoff) + ldsw + _i * 8192), 16, 0, 0); } while (0)
; #define PG8_LDA(dst, b, h) do { _Pragma("unroll") for (int m = 0; m < 4; ++m) _Pragma("unroll") for (int k = 0; k < 2; ++k) dst[m][k] = *(const PG8_LAS bf16x8*)(lds + PG8_SA(b, h) + aoff + m * 2048 + k * 1024); } while (0)
; #define PG8_MMA(ai, bj, At, Bt) do { __builtin_amdgcn_s_setprio(1); _Pragma("unroll") for (int m = 0; m < 4; ++m) _Pragma("unroll") for (int n = 0; n < 2; ++n) _Pragma("unroll") for (int k = 0; k < 2; ++k) \
;         acc[ai][bj][m][n] = __builtin_amdgcn_mfma_f32_16x16x32_bf16(Bt[n][k], At[m][k], acc[ai][bj][m][n], 0, 0, 0); __builtin_amdgcn_s_setprio(0); } while (0)
; #define PG8_WAIT_V(n) asm volatile("s_waitcnt vmcnt(" #n ")" ::: "memory")
; #define PG8_WAIT_L(n) asm volatile("s_waitcnt lgkmcnt(" #n ")" ::: "memory")
; #define PG8_BAR __builtin_amdgcn_s_barrier()
; #define PG8_SCHED __builtin_amdgcn_sched_barrier(0)
; template <class Epi, class Sched, bool ALIGN_EPI = false, bool SP2 = false>
; __device__ __forceinline__ void gemm_phase(PG8_LAS unsigned char* lds, const int tid, const Gemm g, const Sched& S, const Epi& E) {
;     ...
;             PG8_WAIT_V(8); PG8_WAIT_L(0); PG8_BAR; PG8_MMA(0, 0, At, B0); PG8_MMA(0, 1, At, B1); PG8_BAR; PG8_SCHED;
;             PG8_LDA(At, 1, 1); PG8_STAGE(PG8_SB(1, 0), b3, voffB); PG8_STAGE(PG8_SB(1, 1), b3 + hstep, voffB); PG8_STAGE(PG8_SA(1, 0), a3, voffA);
;             PG8_WAIT_V(8); PG8_WAIT_L(0); PG8_BAR; PG8_MMA(1, 0, At, B0); PG8_MMA(1, 1, At, B1); PG8_BAR; PG8_SCHED;
;     ...
;         if constexpr (ALIGN_EPI) { if (wr == 0) PG8_BAR; }
	s_add_i32 s26, s49, s12
	v_lshl_add_u64 v[234:235], v[234:235], 0, s[36:37]
	s_mov_b32 m0, s26
	ds_read_b128 v[194:197], v161 offset:49152
	ds_read_b128 v[198:201], v249 offset:49152
	ds_read_b128 v[202:205], v161 offset:51200
	ds_read_b128 v[206:209], v249 offset:51200
	ds_read_b128 v[210:213], v161 offset:53248
	ds_read_b128 v[214:217], v249 offset:53248
	ds_read_b128 v[218:221], v161 offset:55296
	ds_read_b128 v[230:233], v249 offset:55296
	global_load_lds_dwordx4 v[234:235], off
	s_add_i32 m0, s26, 0x2000
	s_add_u32 s24, s24, 0x40080
	v_lshl_add_u64 v[234:235], v[236:237], 0, s[36:37]
	s_addc_u32 s25, s25, 0
	s_add_i32 s26, s50, s12
	global_load_lds_dwordx4 v[234:235], off
	v_lshl_add_u64 v[234:235], s[24:25], 0, v[168:169]
	s_mov_b32 m0, s26
	s_nop 0
	global_load_lds_dwordx4 v[234:235], off
	v_lshl_add_u64 v[234:235], s[24:25], 0, v[144:145]
	s_add_i32 m0, s26, 0x2000
	s_nop 0
	global_load_lds_dwordx4 v[234:235], off
	v_lshl_add_u64 v[234:235], v[238:239], 0, s[36:37]
	s_mov_b32 m0, s18
	s_nop 0
	global_load_lds_dwordx4 v[234:235], off
	v_lshl_add_u64 v[234:235], v[240:241], 0, s[36:37]
	s_mov_b32 m0, s19
	s_nop 0
	global_load_lds_dwordx4 v[234:235], off
	s_waitcnt vmcnt(8)
	s_waitcnt lgkmcnt(0)
	s_barrier
	s_setprio 1
	s_waitcnt lgkmcnt(0)
	v_mfma_f32_16x16x32_bf16 v[60:63], v[64:67], v[194:197], v[60:63]
	v_mfma_f32_16x16x32_bf16 v[56:59], v[72:75], v[194:197], v[56:59]
	v_mfma_f32_16x16x32_bf16 v[44:47], v[64:67], v[202:205], v[44:47]
	v_mfma_f32_16x16x32_bf16 v[40:43], v[72:75], v[202:205], v[40:43]
	v_mfma_f32_16x16x32_bf16 v[28:31], v[64:67], v[210:213], v[28:31]
	v_mfma_f32_16x16x32_bf16 v[24:27], v[72:75], v[210:213], v[24:27]
	v_mfma_f32_16x16x32_bf16 v[12:15], v[64:67], v[218:221], v[12:15]
	v_mfma_f32_16x16x32_bf16 v[8:11], v[72:75], v[218:221], v[8:11]
	v_mfma_f32_16x16x32_bf16 v[60:63], v[68:71], v[198:201], v[60:63]
	v_mfma_f32_16x16x32_bf16 v[56:59], v[76:79], v[198:201], v[56:59]
	v_mfma_f32_16x16x32_bf16 v[44:47], v[68:71], v[206:209], v[44:47]
	v_mfma_f32_16x16x32_bf16 v[40:43], v[76:79], v[206:209], v[40:43]
	v_mfma_f32_16x16x32_bf16 v[28:31], v[68:71], v[214:217], v[28:31]
	v_mfma_f32_16x16x32_bf16 v[24:27], v[76:79], v[214:217], v[24:27]
	v_mfma_f32_16x16x32_bf16 v[12:15], v[68:71], v[230:233], v[12:15]
	v_mfma_f32_16x16x32_bf16 v[8:11], v[76:79], v[230:233], v[8:11]
	s_setprio 0
	s_setprio 1
	v_mfma_f32_16x16x32_bf16 v[52:55], v[154:157], v[194:197], v[52:55]
	v_mfma_f32_16x16x32_bf16 v[48:51], v[186:189], v[194:197], v[48:51]
	v_mfma_f32_16x16x32_bf16 v[36:39], v[154:157], v[202:205], v[36:39]
	v_mfma_f32_16x16x32_bf16 v[32:35], v[186:189], v[202:205], v[32:35]
	v_mfma_f32_16x16x32_bf16 v[20:23], v[154:157], v[210:213], v[20:23]
	v_mfma_f32_16x16x32_bf16 v[16:19], v[186:189], v[210:213], v[16:19]
	v_mfma_f32_16x16x32_bf16 v[4:7], v[154:157], v[218:221], v[4:7]
	v_mfma_f32_16x16x32_bf16 v[0:3], v[186:189], v[218:221], v[0:3]
	v_mfma_f32_16x16x32_bf16 v[52:55], v[164:167], v[198:201], v[52:55]
	v_mfma_f32_16x16x32_bf16 v[48:51], v[190:193], v[198:201], v[48:51]
	v_mfma_f32_16x16x32_bf16 v[36:39], v[164:167], v[206:209], v[36:39]
	v_mfma_f32_16x16x32_bf16 v[32:35], v[190:193], v[206:209], v[32:35]
	v_mfma_f32_16x16x32_bf16 v[20:23], v[164:167], v[214:217], v[20:23]
	v_mfma_f32_16x16x32_bf16 v[16:19], v[190:193], v[214:217], v[16:19]
	v_mfma_f32_16x16x32_bf16 v[4:7], v[164:167], v[230:233], v[4:7]
	v_mfma_f32_16x16x32_bf16 v[0:3], v[190:193], v[230:233], v[0:3]
	s_setprio 0
	s_barrier
	s_add_i32 s48, s48, 2
	s_add_u32 s4, s4, 0x100
	s_addc_u32 s5, s5, 0
	s_add_u32 s46, s46, 0x100
	s_addc_u32 s47, s47, 0
	s_cmp_gt_u32 s48, 13
	s_cbranch_scc0 .LBB0_426
	s_and_b64 vcc, exec, s[28:29]
	s_cbranch_vccz .LBB0_429
	s_barrier

; #define LAS __attribute__((address_space(3)))
; __global__ void __launch_bounds__(NTHR, 2) fwd_megakernel(Args a) {
;     extern __shared__ __attribute__((aligned(16))) unsigned char lds_raw[];
;     LAS unsigned char* lds = (LAS unsigned char*)lds_raw;
	.amdhsa_kernel _Z14fwd_megakernel4Args
		.amdhsa_group_segment_fixed_size 0
		.amdhsa_private_segment_fixed_size 0
		.amdhsa_kernarg_size 384
		.amdhsa_user_sgpr_count 2
		.amdhsa_user_sgpr_dispatch_ptr 0
		.amdhsa_user_sgpr_queue_ptr 0
		.amdhsa_user_sgpr_kernarg_segment_ptr 1
		.amdhsa_user_sgpr_dispatch_id 0
		.amdhsa_user_sgpr_kernarg_preload_length 0
		.amdhsa_user_sgpr_kernarg_preload_offset 0
		.amdhsa_user_sgpr_private_segment_size 0
		.amdhsa_uses_dynamic_stack 0
		.amdhsa_enable_private_segment 0
		.amdhsa_system_sgpr_workgroup_id_x 1
		.amdhsa_system_sgpr_workgroup_id_y 0
		.amdhsa_system_sgpr_workgroup_id_z 0
		.amdhsa_system_sgpr_workgroup_info 0
		.amdhsa_system_vgpr_workitem_id 2
		.amdhsa_next_free_vgpr 256
		.amdhsa_next_free_sgpr 100
		.amdhsa_accum_offset 256
		.amdhsa_reserve_vcc 1
		.amdhsa_float_round_mode_32 0
		.amdhsa_float_round_mode_16_64 0
		.amdhsa_float_denorm_mode_32 3
		.amdhsa_float_denorm_mode_16_64 3
		.amdhsa_dx10_clamp 1
		.amdhsa_ieee_mode 1
		.amdhsa_fp16_overflow 0
		.amdhsa_tg_split 0
		.amdhsa_exception_fp_ieee_invalid_op 0
		.amdhsa_exception_fp_denorm_src 0
		.amdhsa_exception_fp_ieee_div_zero 0
		.amdhsa_exception_fp_ieee_overflow 0
		.amdhsa_exception_fp_ieee_underflow 0
		.amdhsa_exception_fp_ieee_inexact 0
		.amdhsa_exception_int_div_zero 0
	.end_amdhsa_kernel

; #define LAS __attribute__((address_space(3)))
; __global__ void __launch_bounds__(NTHR, 2) fwd_megakernel(Args a) {
;     extern __shared__ __attribute__((aligned(16))) unsigned char lds_raw[];
;     LAS unsigned char* lds = (LAS unsigned char*)lds_raw;
amdhsa.kernels:
  - .agpr_count:     0
    .args:
      - .offset:         0
        .size:           128
        .value_kind:     by_value
      - .offset:         128
        .size:           4
        .value_kind:     hidden_block_count_x
      - .offset:         132
        .size:           4
        .value_kind:     hidden_block_count_y
      - .offset:         136
        .size:           4
        .value_kind:     hidden_block_count_z
      - .offset:         140
        .size:           2
        .value_kind:     hidden_group_size_x
      - .offset:         142
        .size:           2
        .value_kind:     hidden_group_size_y
      - .offset:         144
        .size:           2
        .value_kind:     hidden_group_size_z
      - .offset:         146
        .size:           2
        .value_kind:     hidden_remainder_x
      - .offset:         148
        .size:           2
        .value_kind:     hidden_remainder_y
      - .offset:         150
        .size:           2
        .value_kind:     hidden_remainder_z
      - .offset:         168
        .size:           8
        .value_kind:     hidden_global_offset_x
      - .offset:         176
        .size:           8
        .value_kind:     hidden_global_offset_y
      - .offset:         184
        .size:           8
        .value_kind:     hidden_global_offset_z
      - .offset:         192
        .size:           2
        .value_kind:     hidden_grid_dims
      - .offset:         216
        .size:           8
        .value_kind:     hidden_multigrid_sync_arg
      - .offset:         248
        .size:           4
        .value_kind:     hidden_dynamic_lds_size
    .group_segment_fixed_size: 0
    .kernarg_segment_align: 8
    .kernarg_segment_size: 384
    .language:       OpenCL C
    .language_version:
      - 2
      - 0
    .max_flat_workgroup_size: 512
    .name:           _Z14fwd_megakernel4Args
    .private_segment_fixed_size: 0
    .sgpr_count:     106
    .sgpr_spill_count: 255
    .symbol:         _Z14fwd_megakernel4Args.kd
    .uniform_work_group_size: 1
    .uses_dynamic_stack: false
    .vgpr_count:     256
    .vgpr_spill_count: 0
    .wavefront_size: 64
